# full deferral of w_up/w_down layers 1-3 into barrier waits (10-barrier windows), plus canon + EpiRes prefetch
# baseline (speedup 1.0000x reference)
; #define LAS __attribute__((address_space(3)))
; #define LDS_WAIT() asm volatile("s_waitcnt lgkmcnt(0)" ::: "memory")
; __device__ __forceinline__ void transpose_item(const float* W, const float* g  , int K, int N, bf16* WT, LAS float* scr, int kb, int nb, int lane) {
;     const int k0 = 64 * kb, n0 = 32 * nb;
; #pragma unroll 8
;     for (int i = 0; i < 32; ++i) { const int kk = 2 * i + (lane >> 5); const float gv = g ? g[k0 + kk] : 1.f; scr[kk * 33 + (lane & 31)] = W[(size_t)(k0 + kk) * N + n0 + (lane & 31)] * gv; }
;     LDS_WAIT(); asm volatile("" ::: "memory");
;     const int c = lane & 7;
; #pragma unroll
;     for (int j = 0; j < 4; ++j) { const int n = (lane >> 3) + 8 * j; const LAS float* s = scr + (8 * c) * 33 + n;
; __global__ void __launch_bounds__(NWAVES * 64, 2) fwd(Args args) {
;     ...
;     PH_BEGIN
;         LAS float* scr = (LAS float*)(L + RING_OFF + wave * 16384);
;         for (int rep_ = 0; rep_ < R_PRO; ++rep_) {
;         transpose_tensor(ka->in[8], ka->in[4], 2 * DM, 2, DM, NQKV, WSB(WS_WQKVA), scr, gw, NGW, lane);
.LBB0_13:
.LBB0_14:
	v_readlane_b32 s10, v252, 0
	v_readlane_b32 s11, v252, 1
	s_mov_b32 s61, 0
	v_writelane_b32 v255, s61, 6
	v_lshrrev_b32_e32 v100, 6, v0
	v_and_b32_e32 v101, 63, v0
	s_load_dwordx2 s[12:13], s[10:11], 0xd0
	v_readfirstlane_b32 s14, v100
	v_lshrrev_b32_e32 v102, 5, v101
	v_and_b32_e32 v103, 31, v101
	v_and_b32_e32 v105, 7, v101
	v_lshrrev_b32_e32 v106, 3, v101
	s_lshl_b32 s15, s59, 3
	s_add_i32 s15, s15, s14
	s_lshl_b32 s16, s60, 3
	s_lshl_b32 s17, s14, 14
	s_mul_i32 s69, s60, 70
	s_min_u32 s69, s69, 0x4000
	s_min_u32 s67, s69, 0x2000
	s_max_u32 s68, s69, 0x2000
	s_sub_u32 s68, s68, 0x2000
	v_mad_u32_u24 v104, v102, 33, v103
	v_lshl_add_u32 v104, v104, 2, s17
	v_mul_u32_u24_e32 v107, 0x108, v105
	v_add_u32_e32 v107, v107, v106
	v_lshl_add_u32 v107, v107, 2, s17
	v_lshlrev_b32_e32 v108, 5, v105
	v_lshlrev_b32_e32 v109, 2, v103
	v_lshlrev_b32_e32 v105, 4, v105
	s_mov_b32 s18, 0
	s_waitcnt lgkmcnt(0)

; #define LAS __attribute__((address_space(3)))
; __device__ __forceinline__ void transpose_tensor(const float* W, const float* g, int gstep, int nl, int K, int N, bf16* WT, LAS float* scr, int gw, int NGW, int lane) {
;     const int nblk = N / 32, per = (K / 64) * nblk, total = nl * per;
;     for (int it = gw; it < total; it += NGW) { const int l = it / per, r = it - l * per;
;         transpose_item(W + (size_t)l * K * N, g ? g + (size_t)l * gstep : nullptr, K, N, WT + (size_t)l * K * N, scr, r / nblk, r % nblk, lane); }
; __global__ void __launch_bounds__(NWAVES * 64, 2) fwd(Args args) {
;     ...
;         transpose_tensor(ka->in[23], ka->in[7], DM, 4, DM, DFF, WSB(WS_WUP), scr, gw, NGW, lane);
;         transpose_tensor(ka->in[24], nullptr, 0, 4, DFF, DM, WSB(WS_WDN), scr, gw, NGW, lane);
.Lwt_p9:
	s_movk_i32 s19, 0xb8
	s_mov_b32 s62, 0x800
	s_mov_b32 s63, 0x2000
	s_mov_b32 s26, 0x80000
	s_mov_b32 s28, 0x1000000
	s_mov_b32 s34, 0x11000000
	s_add_u32 s65, s67, 0x2000
	s_mov_b32 s66, 0x4000
	s_cmp_lt_u32 s65, s66
	s_cbranch_scc0 .Lwt_next
	s_movk_i32 s20, 0x38
	s_mov_b32 s21, 0x0
	s_mov_b32 s22, 0x2000
	s_mov_b32 s23, 1
	s_branch .Lwt_run
.Lwt_p10:
	s_movk_i32 s19, 0xc0
	s_mov_b32 s62, 0x2000
	s_mov_b32 s63, 0x800
	s_mov_b32 s26, 0x80000
	s_mov_b32 s28, 0x4000000
	s_mov_b32 s34, 0x19000000
	s_add_u32 s65, s68, 0x2000
	s_mov_b32 s66, 0x4000
	s_cmp_lt_u32 s65, s66
	s_cbranch_scc0 .Lwt_next
	s_movk_i32 s20, 0x20
	s_mov_b32 s21, 0
	s_mov_b32 s22, 0
	s_mov_b32 s23, 0
	s_branch .Lwt_run
.Lwt_p11:
	s_movk_i32 s19, 0xb8
	s_mov_b32 s62, 0x800
	s_mov_b32 s63, 0x2000
	s_mov_b32 s26, 0x80000
	s_mov_b32 s28, 0x1000000
	s_mov_b32 s34, 0x11000000
	s_add_u32 s65, s67, 0x4000
	s_mov_b32 s66, 0x6000
	s_cmp_lt_u32 s65, s66
	s_cbranch_scc0 .Lwt_next
	s_movk_i32 s20, 0x38
	s_mov_b32 s21, 0x0
	s_mov_b32 s22, 0x2000
	s_mov_b32 s23, 1
	s_branch .Lwt_run
.Lwt_p12:
	s_movk_i32 s19, 0xc0
	s_mov_b32 s62, 0x2000
	s_mov_b32 s63, 0x800
	s_mov_b32 s26, 0x80000
	s_mov_b32 s28, 0x4000000
	s_mov_b32 s34, 0x19000000
	s_add_u32 s65, s68, 0x4000
	s_mov_b32 s66, 0x6000
	s_cmp_lt_u32 s65, s66
	s_cbranch_scc0 .Lwt_next
	s_movk_i32 s20, 0x20
	s_mov_b32 s21, 0
	s_mov_b32 s22, 0
	s_mov_b32 s23, 0
	s_branch .Lwt_run
.Lwt_p13:
	s_movk_i32 s19, 0xb8
	s_mov_b32 s62, 0x800
	s_mov_b32 s63, 0x2000
	s_mov_b32 s26, 0x80000
	s_mov_b32 s28, 0x1000000
	s_mov_b32 s34, 0x11000000
	s_add_u32 s65, s67, 0x6000
	s_mov_b32 s66, 0x8000
	s_cmp_lt_u32 s65, s66
	s_cbranch_scc0 .Lwt_next
	s_movk_i32 s20, 0x38
	s_mov_b32 s21, 0x0
	s_mov_b32 s22, 0x2000
	s_mov_b32 s23, 1
	s_branch .Lwt_run
.Lwt_p14:
	s_movk_i32 s19, 0xc0
	s_mov_b32 s62, 0x2000
	s_mov_b32 s63, 0x800
	s_mov_b32 s26, 0x80000
	s_mov_b32 s28, 0x4000000
	s_mov_b32 s34, 0x19000000
	s_add_u32 s65, s68, 0x6000
	s_mov_b32 s66, 0x8000
	s_cmp_lt_u32 s65, s66
	s_cbranch_scc0 .Lwt_next
	s_movk_i32 s20, 0x20
	s_mov_b32 s21, 0
	s_mov_b32 s22, 0
	s_mov_b32 s23, 0
	s_branch .Lwt_run

; #define LAS __attribute__((address_space(3)))
; __device__ __forceinline__ void transpose_tensor(const float* W, const float* g, int gstep, int nl, int K, int N, bf16* WT, LAS float* scr, int gw, int NGW, int lane) {
;     const int nblk = N / 32, per = (K / 64) * nblk, total = nl * per;
;     for (int it = gw; it < total; it += NGW) { const int l = it / per, r = it - l * per;
;         transpose_item(W + (size_t)l * K * N, g ? g + (size_t)l * gstep : nullptr, K, N, WT + (size_t)l * K * N, scr, r / nblk, r % nblk, lane); }
; __global__ void __launch_bounds__(NWAVES * 64, 2) fwd(Args args) {
;     ...
;         transpose_tensor(ka->in[23], ka->in[7], DM, 4, DM, DFF, WSB(WS_WUP), scr, gw, NGW, lane);
;         transpose_tensor(ka->in[24], nullptr, 0, 4, DFF, DM, WSB(WS_WDN), scr, gw, NGW, lane);
.Lwb_entry:
	v_readlane_b32 s96, v255, 6
	v_readfirstlane_b32 s94, v0
	s_add_u32 s95, s96, 1
	s_lshr_b32 s94, s94, 6
	v_writelane_b32 v255, s95, 6
	s_cmp_eq_u32 s94, 0
	s_cbranch_scc1 .Lwb_ret
	s_mov_b32 s85, 1
	s_mov_b32 s84, s96
	s_cmp_lt_u32 s84, 10
	s_cbranch_scc1 .Lwb_go
	s_mov_b32 s85, 2
	s_sub_u32 s84, s96, 10
	s_cmp_lt_u32 s84, 10
	s_cbranch_scc1 .Lwb_go
	s_mov_b32 s85, 3
	s_sub_u32 s84, s96, 20
	s_cmp_lt_u32 s84, 10
	s_cbranch_scc1 .Lwb_go
	s_branch .Lwb_ret
.Lwb_go:
	s_mul_i32 s83, s60, 7
	s_mul_i32 s84, s84, s83
	s_mul_i32 s83, s59, 7
	s_add_u32 s84, s84, s83
	s_add_u32 s84, s84, s94
	s_sub_u32 s84, s84, 1
	s_mul_i32 s69, s60, 70
	s_min_u32 s69, s69, 0x4000
	s_cmp_lt_u32 s84, s69
	s_cbranch_scc0 .Lwb_ret
	v_readlane_b32 s92, v252, 0
	v_readlane_b32 s93, v252, 1
	s_load_dwordx2 s[90:91], s[92:93], 0xd0
	s_cmp_lt_u32 s84, 0x2000
	s_cbranch_scc0 .Lwb_dn
	s_load_dwordx2 s[88:89], s[92:93], 0xb8
	s_load_dwordx2 s[86:87], s[92:93], 0x38
	s_lshr_b32 s83, s84, 8
	s_and_b32 s82, s84, 0xff
	s_mov_b32 s73, 0x8000
	s_mov_b32 s72, 0x1000
	s_mov_b32 s78, 0x200000
	s_mov_b32 s77, 0x20000
	s_mov_b32 s75, 0x11000000
	s_mov_b32 s74, 1
	s_branch .Lwb_cm
